# retention in-loop prefetch: scalar base + per-lane 32-bit offsets (no VALU 64-bit address math per chunk), on v48
# baseline (speedup 1.0000x reference)
; #define LAS __attribute__((address_space(3)))
; __device__ __forceinline__ void ret_mfma(const Params& P, LAS unsigned char* lds, int wave) {
;     ...
;     for (int unit = blockIdx.x; unit < 256; unit += gridDim.x) {
;         const int xcd_ = unit & 7, idx_ = unit >> 3, bh = xcd_ * 4 + (idx_ >> 3), slice = idx_ & 7, b = bh >> 2, hh = bh & 3;
;         const float gam = 1.f - exp2f(-5.f - (float)hh), lg = log2f(gam), g64 = exp2f(lg * 64.f);
;         for (int i = t; i < 33792 / 16; i += NTHREADS) *(LAS u32x4*)(lds + ST_OFF + i * 16) = (u32x4){0u, 0u, 0u, 0u};
;         f32x16 st[2];
; #pragma unroll
;         for (int a = 0; a < 2; ++a)
; #pragma unroll
;             for (int i = 0; i < 16; ++i) st[a][i] = 0.f;
;         const size_t rb = (size_t)b * SEQ;
;         float dec[16];
;         { const int mblk = (wave & 3) >> 1, nblk = wave & 1, n = nblk * 32 + q32;
; #pragma unroll
;           for (int i = 0; i < 16; ++i) { const int mm = mblk * 32 + 8 * (i >> 2) + 4 * hf + (i & 3); const int dist = n > mm ? n - mm : mm - n;
;               dec[i] = wave < 4 ? __builtin_amdgcn_exp2f(lg * (float)(dist - (63 - mm))) : __builtin_amdgcn_exp2f(lg * (float)(n + 1)); } }
;         u32x4 pq[4], pkk[4], pvv;
;         const int vr = t >> 3, vc = t & 7;
; #pragma unroll
;         for (int i = 0; i < 4; ++i) { const int id = t + 512 * i, r = id >> 5, ch = id & 31;
;             pq[i] = *(const u32x4*)(QK + (rb + r) * 2048 + hh * 256 + ch * 8); pkk[i] = *(const u32x4*)(QK + (rb + r) * 2048 + 1024 + hh * 256 + ch * 8); }
;         pvv = *(const u32x4*)(V + (rb + vr) * 2048 + hh * 512 + slice * 64 + vc * 8);
; #pragma unroll 1
;         for (int c = 0; c < 64; ++c) {
; #pragma unroll
;             for (int i = 0; i < 4; ++i) { const int id = t + 512 * i, r = id >> 5, ch = id & 31;
;                 *(LAS u32x4*)(lds + Q_OFF + r * QP + ch * 16) = pq[i]; *(LAS u32x4*)(lds + K_OFF + r * QP + ch * 16) = pkk[i]; }
;             *(LAS u32x4*)(lds + V_OFF + vr * VP + vc * 16) = pvv;
;             __syncthreads();
;             if (c + 1 < 64) { const size_t r1 = rb + (size_t)(c + 1) * 64;
; #pragma unroll
;                 for (int i = 0; i < 4; ++i) { const int id = t + 512 * i, r = id >> 5, ch = id & 31;
;                     pq[i] = *(const u32x4*)(QK + (r1 + r) * 2048 + hh * 256 + ch * 8); pkk[i] = *(const u32x4*)(QK + (r1 + r) * 2048 + 1024 + hh * 256 + ch * 8); }
.LBB0_252:
	s_or_b64 exec, exec, s[8:9]
	s_ashr_i32 s9, s28, 6
	s_and_b32 s23, s9, 3
	v_cvt_f32_ubyte0_e32 v0, s23
	v_sub_f32_e32 v0, 0xc0a00000, v0
	v_cmp_gt_f32_e32 vcc, s25, v0
	s_lshl_b32 s8, s28, 2
	s_and_b32 s8, s8, 28
	v_cndmask_b32_e32 v1, 0, v182, vcc
	v_add_f32_e32 v0, v0, v1
	s_add_i32 s8, s8, s9
	v_exp_f32_e32 v0, v0
	s_bfe_u32 s22, s28, 0x30003
	s_ashr_i32 s8, s8, 2
	s_and_b64 s[18:19], vcc, exec
	s_cselect_b32 s9, 0xffffffc0, 0
	v_ldexp_f32 v0, v0, s9
	v_sub_f32_e32 v0, 1.0, v0
	v_cmp_gt_f32_e32 vcc, s26, v0
	s_and_b64 s[18:19], vcc, exec
	s_cselect_b32 s9, 32, 0
	v_ldexp_f32 v0, v0, s9
	v_log_f32_e32 v2, v0
	v_cndmask_b32_e32 v1, 0, v183, vcc
	s_mov_b32 s21, s15
	v_mov_b32_e32 v103, v91
	v_sub_f32_e32 v1, v2, v1
	v_mul_f32_e32 v2, 0x42800000, v1
	v_cmp_gt_f32_e32 vcc, s25, v2
	s_and_b64 s[18:19], vcc, exec
	s_cselect_b32 s9, 0xffffffc0, 0
	v_cndmask_b32_e32 v2, 0, v182, vcc
	v_fmac_f32_e32 v2, 0x42800000, v1
	v_exp_f32_e32 v2, v2
	v_mul_f32_e32 v3, v1, v85
	v_mul_f32_e32 v4, v1, v152
	v_exp_f32_e32 v3, v3
	v_ldexp_f32 v106, v2, s9
	v_mul_f32_e32 v2, v1, v153
	v_exp_f32_e32 v105, v2
	v_mul_f32_e32 v2, v1, v154
	v_exp_f32_e32 v110, v2
	v_mul_f32_e32 v2, v1, v155
	v_exp_f32_e32 v111, v2
	v_mul_f32_e32 v2, v1, v156
	v_exp_f32_e32 v104, v4
	v_exp_f32_e32 v112, v2
	v_mul_f32_e32 v2, v1, v157
	v_exp_f32_e32 v113, v2
	v_mul_f32_e32 v2, v1, v158
	s_ashr_i32 s9, s8, 31
	v_exp_f32_e32 v114, v2
	v_mul_f32_e32 v2, v1, v159
	v_exp_f32_e32 v115, v2
	v_mul_f32_e32 v2, v1, v160
	s_lshl_b64 s[18:19], s[8:9], 12
	v_cndmask_b32_e64 v108, v3, v104, s[4:5]
	v_exp_f32_e32 v116, v2
	v_lshl_add_u64 v[2:3], s[18:19], 0, v[92:93]
	v_lshlrev_b64 v[2:3], 12, v[2:3]
	v_lshl_add_u64 v[2:3], s[44:45], 0, v[2:3]
	s_lshl_b32 s14, s23, 9
	v_lshl_add_u64 v[2:3], v[2:3], 0, s[14:15]
	v_lshl_add_u64 v[2:3], v[2:3], 0, v[90:91]
	s_waitcnt vmcnt(0)
	flat_load_dwordx4 v[48:51], v[2:3]
	flat_load_dwordx4 v[52:55], v[2:3] offset:2048
	v_lshl_add_u64 v[2:3], s[18:19], 0, v[94:95]
	v_lshlrev_b64 v[2:3], 12, v[2:3]
	v_lshl_add_u64 v[2:3], s[44:45], 0, v[2:3]
	v_lshl_add_u64 v[2:3], v[2:3], 0, s[14:15]
	v_lshl_add_u64 v[2:3], v[2:3], 0, v[90:91]
	flat_load_dwordx4 v[56:59], v[2:3]
	flat_load_dwordx4 v[60:63], v[2:3] offset:2048
	v_lshl_add_u64 v[2:3], s[18:19], 0, v[96:97]
	v_lshlrev_b64 v[2:3], 12, v[2:3]
	v_lshl_add_u64 v[2:3], s[44:45], 0, v[2:3]
	v_lshl_add_u64 v[2:3], v[2:3], 0, s[14:15]
	v_lshl_add_u64 v[2:3], v[2:3], 0, v[90:91]
	flat_load_dwordx4 v[64:67], v[2:3]
	flat_load_dwordx4 v[68:71], v[2:3] offset:2048
	v_lshl_add_u64 v[2:3], s[18:19], 0, v[98:99]
	v_lshlrev_b64 v[2:3], 12, v[2:3]
	v_lshl_add_u64 v[2:3], s[44:45], 0, v[2:3]
	v_lshl_add_u64 v[2:3], v[2:3], 0, s[14:15]
	v_lshl_add_u64 v[2:3], v[2:3], 0, v[90:91]
	flat_load_dwordx4 v[72:75], v[2:3]
	flat_load_dwordx4 v[76:79], v[2:3] offset:2048
	v_lshl_add_u64 v[2:3], s[18:19], 0, v[88:89]
	v_lshlrev_b64 v[2:3], 12, v[2:3]
	v_lshl_add_u64 v[2:3], s[36:37], 0, v[2:3]
	s_lshl_b32 s8, s23, 10
	s_mov_b32 s9, s15
	v_lshl_add_u64 v[2:3], v[2:3], 0, s[8:9]
	s_lshl_b32 s20, s22, 7
	v_lshl_add_u64 v[2:3], v[2:3], 0, s[20:21]
	v_lshl_add_u64 v[2:3], v[2:3], 0, v[102:103]
	flat_load_dwordx4 v[80:83], v[2:3]
	s_add_u32 s8, s36, s8
	s_addc_u32 s9, s37, 0
	s_add_u32 s8, s8, s20
	v_mul_f32_e32 v2, v1, v161
	s_addc_u32 s9, s9, 0
	s_lshl_b32 s20, s23, 6
	v_exp_f32_e32 v117, v2
	v_mul_f32_e32 v2, v1, v162
	s_add_u32 s20, s60, s20
	v_exp_f32_e32 v118, v2
	v_mul_f32_e32 v2, v1, v163
	s_addc_u32 s21, s61, 0
	s_lshl_b32 s22, s22, 3
	v_exp_f32_e32 v119, v2
	v_mul_f32_e32 v2, v1, v164
	s_add_u32 s20, s20, s22
	v_exp_f32_e32 v120, v2
	v_mul_f32_e32 v2, v1, v165
	s_addc_u32 s21, s21, 0
	v_exp_f32_e32 v121, v2
	v_mul_f32_e32 v2, v1, v166
	v_mul_f32_e32 v1, v1, v167
	s_add_u32 s20, s20, s16
	v_exp_f32_e32 v122, v2
	v_exp_f32_e32 v123, v1
	s_addc_u32 s21, s21, s17
	v_lshl_add_u64 v[124:125], s[8:9], 0, v[102:103]
	s_mov_b64 s[62:63], s[8:9]
	s_add_u32 s8, s8, s27
	v_mov_b32_e32 v0, 0
	s_addc_u32 s9, s9, 0
	s_mov_b32 s29, 0
	v_mov_b32_e32 v126, v106
	v_mov_b32_e32 v127, v106
	v_lshl_add_u64 v[128:129], v[86:87], 1, s[8:9]
	v_mov_b32_e32 v109, v108
	v_lshl_add_u64 v[144:145], v[100:101], 0, s[14:15]
	s_add_u32 s66, s44, s14
	s_addc_u32 s67, s45, s15
	v_lshl_add_u32 v138, v92, 12, v90
	v_lshl_add_u32 v139, v94, 12, v90
	v_lshl_add_u32 v140, v96, 12, v90
	v_lshl_add_u32 v141, v98, 12, v90
	v_lshl_add_u32 v185, v88, 12, v102
	v_mov_b32_e32 v1, v0
	v_mov_b32_e32 v2, v0
	v_mov_b32_e32 v3, v0
	v_mov_b32_e32 v4, v0
	v_mov_b32_e32 v5, v0
	v_mov_b32_e32 v6, v0
	v_mov_b32_e32 v7, v0
	v_mov_b32_e32 v8, v0
	v_mov_b32_e32 v9, v0
	v_mov_b32_e32 v10, v0
	v_mov_b32_e32 v11, v0
	v_mov_b32_e32 v12, v0
	v_mov_b32_e32 v13, v0
	v_mov_b32_e32 v14, v0
	v_mov_b32_e32 v15, v0
	v_mov_b32_e32 v16, v0
	v_mov_b32_e32 v17, v0
	v_mov_b32_e32 v18, v0
	v_mov_b32_e32 v19, v0
	v_mov_b32_e32 v20, v0
	v_mov_b32_e32 v21, v0
	v_mov_b32_e32 v22, v0
	v_mov_b32_e32 v23, v0
	v_mov_b32_e32 v24, v0
	v_mov_b32_e32 v25, v0
	v_mov_b32_e32 v26, v0
	v_mov_b32_e32 v27, v0
	v_mov_b32_e32 v28, v0
	v_mov_b32_e32 v29, v0
	v_mov_b32_e32 v30, v0
	v_mov_b32_e32 v31, v0
	s_add_u32 s8, s18, 64
	s_addc_u32 s9, s19, 0
	v_lshl_add_u64 v[32:33], s[8:9], 0, v[92:93]
	v_lshlrev_b64 v[32:33], 12, v[32:33]
	v_lshl_add_u64 v[32:33], v[144:145], 0, v[32:33]
	global_load_dwordx4 v[226:229], v[32:33], off
	global_load_dwordx4 v[230:233], v[32:33], off offset:2048
	v_lshl_add_u64 v[32:33], s[8:9], 0, v[94:95]
	v_lshlrev_b64 v[32:33], 12, v[32:33]
	v_lshl_add_u64 v[32:33], v[144:145], 0, v[32:33]
	global_load_dwordx4 v[234:237], v[32:33], off
	global_load_dwordx4 v[238:241], v[32:33], off offset:2048
	v_lshl_add_u64 v[32:33], s[8:9], 0, v[96:97]
	v_lshlrev_b64 v[32:33], 12, v[32:33]
	v_lshl_add_u64 v[32:33], v[144:145], 0, v[32:33]
	global_load_dwordx4 v[246:249], v[32:33], off
	global_load_dwordx4 v[250:253], v[32:33], off offset:2048
	v_lshl_add_u64 v[32:33], s[8:9], 0, v[98:99]
	v_lshlrev_b64 v[32:33], 12, v[32:33]
	v_lshl_add_u64 v[32:33], v[144:145], 0, v[32:33]
	global_load_dwordx4 v[206:209], v[32:33], off
	global_load_dwordx4 v[130:133], v[32:33], off offset:2048
	v_lshl_add_u64 v[32:33], s[8:9], 0, v[88:89]
	v_lshlrev_b64 v[32:33], 12, v[32:33]
	v_lshl_add_u64 v[32:33], v[124:125], 0, v[32:33]
	global_load_dwordx4 v[134:137], v[32:33], off
	s_waitcnt vmcnt(0)
	s_branch .LBB0_255

; #define LAS __attribute__((address_space(3)))
; __device__ __forceinline__ void ret_mfma(const Params& P, LAS unsigned char* lds, int wave) {
;     ...
;         for (int c = 0; c < 64; ++c) {
; #pragma unroll
;             for (int i = 0; i < 4; ++i) { const int id = t + 512 * i, r = id >> 5, ch = id & 31;
;                 *(LAS u32x4*)(lds + Q_OFF + r * QP + ch * 16) = pq[i]; *(LAS u32x4*)(lds + K_OFF + r * QP + ch * 16) = pkk[i]; }
;             *(LAS u32x4*)(lds + V_OFF + vr * VP + vc * 16) = pvv;
;             __syncthreads();
;             if (c + 1 < 64) { const size_t r1 = rb + (size_t)(c + 1) * 64;
; #pragma unroll
;                 for (int i = 0; i < 4; ++i) { const int id = t + 512 * i, r = id >> 5, ch = id & 31;
;                     pq[i] = *(const u32x4*)(QK + (r1 + r) * 2048 + hh * 256 + ch * 8); pkk[i] = *(const u32x4*)(QK + (r1 + r) * 2048 + 1024 + hh * 256 + ch * 8); }
;                 pvv = *(const u32x4*)(V + (r1 + vr) * 2048 + hh * 512 + slice * 64 + vc * 8); }
.Lret_wait_done:
	v_mov_b64_e32 v[48:49], v[226:227]
	v_mov_b64_e32 v[50:51], v[228:229]
	v_mov_b64_e32 v[52:53], v[230:231]
	v_mov_b64_e32 v[54:55], v[232:233]
	v_mov_b64_e32 v[56:57], v[234:235]
	v_mov_b64_e32 v[58:59], v[236:237]
	v_mov_b64_e32 v[60:61], v[238:239]
	v_mov_b64_e32 v[62:63], v[240:241]
	v_mov_b64_e32 v[64:65], v[246:247]
	v_mov_b64_e32 v[66:67], v[248:249]
	v_mov_b64_e32 v[68:69], v[250:251]
	v_mov_b64_e32 v[70:71], v[252:253]
	v_mov_b64_e32 v[72:73], v[206:207]
	v_mov_b64_e32 v[74:75], v[208:209]
	v_mov_b64_e32 v[76:77], v[130:131]
	v_mov_b64_e32 v[78:79], v[132:133]
	v_mov_b64_e32 v[80:81], v[134:135]
	v_mov_b64_e32 v[82:83], v[136:137]
	s_cmp_lt_u32 s29, 62
	s_cbranch_scc0 .LBB0_257
	s_lshl_b32 s8, s14, 6
	s_add_i32 s8, s8, 64
	s_add_u32 s8, s18, s8
	s_addc_u32 s9, s19, 0
	s_lshl_b64 s[8:9], s[8:9], 12
	s_add_u32 s30, s8, s66
	s_addc_u32 s31, s9, s67
	s_add_u32 s34, s8, s62
	s_addc_u32 s35, s9, s63
	global_load_dwordx4 v[226:229], v138, s[30:31]
	global_load_dwordx4 v[230:233], v138, s[30:31] offset:2048
	global_load_dwordx4 v[234:237], v139, s[30:31]
	global_load_dwordx4 v[238:241], v139, s[30:31] offset:2048
	global_load_dwordx4 v[246:249], v140, s[30:31]
	global_load_dwordx4 v[250:253], v140, s[30:31] offset:2048
	global_load_dwordx4 v[206:209], v141, s[30:31]
	global_load_dwordx4 v[130:133], v141, s[30:31] offset:2048
	global_load_dwordx4 v[134:137], v185, s[34:35]
